# v89 + attention tile code: packed f32 VALU beside MFMAs (v_pk_add/v_pk_mul) split into scalar halves (191 sites)
# speedup vs baseline: 1.0086x; 1.0086x over previous
; #define LAS __attribute__((address_space(3)))
; template <int MODE, int NDG> ...
;     ...
;         const bf16x8 a0 = lds16(kp), a1 = lds16(kp + 32 * 144);
;         p0 = __builtin_amdgcn_mfma_f32_32x32x16_bf16(a0, qr[0], MODE == MODE_SB ? z : negm, 0, 0, 0);
;         p1 = __builtin_amdgcn_mfma_f32_32x32x16_bf16(a1, qr[0], MODE == MODE_SB ? z : negm, 0, 0, 0); }
; #pragma unroll
;     for (int d0 = 1; d0 < 4; ++d0) {
;         const bf16x8 a0 = lds16(kp + d0 * 32), a1 = lds16(kp + 32 * 144 + d0 * 32);
;         p0 = __builtin_amdgcn_mfma_f32_32x32x16_bf16(a0, qr[d0], p0, 0, 0, 0);
;         p1 = __builtin_amdgcn_mfma_f32_32x32x16_bf16(a1, qr[d0], p1, 0, 0, 0);
;     }
;     ...
;     if (MODE == MODE_DIFF) { f32x16 d0_ = p0, d1_ = p1;
; #pragma unroll
;         for (int d0 = 0; d0 < 4; ++d0) { d0_ = __builtin_amdgcn_mfma_f32_32x32x16_bf16(qr[d0], qr[d0], d0_, 0, 0, 0); d1_ = __builtin_amdgcn_mfma_f32_32x32x16_bf16(qr[d0], qr[d0], d1_, 0, 0, 0); }
;         asm volatile("" :: "v"(d0_), "v"(d1_)); }
;     ...
;     if (MODE == MODE_DIFF) {
; #pragma unroll
;         for (int d0 = 0; d0 < 4; ++d0) { const bf16x8 a0 = lds16(kp + d0 * 32 + 64 * 144), a1 = lds16(kp + 32 * 144 + d0 * 32 + 64 * 144); asm volatile("" :: "v"(a0), "v"(a1)); }
;         LAS const unsigned char* vq = vst + ((lane >> 4) & 1) * 32 + (lane & 3) * 8 + (4 * hi + ((lane & 15) >> 2)) * 64;
; #pragma unroll
;         for (int i = 0; i < 8; ++i) { const bf16x8 vf = vfrag(vq + i * 1024); asm volatile("" :: "v"(vf)); } }
;     ...
;     if (MODE == MODE_FOX) {
;         const bf16x8 a0 = lds16(ast + r32 * 16), a1 = lds16(ast + (32 + r32) * 16);
;         const short one = hi ? (short)0 : (short)0x3F80;
;         const bf16x8 qa = (bf16x8){one, one, one, 0, 0, 0, 0, 0};
;         p0 = __builtin_amdgcn_mfma_f32_32x32x16_bf16(a0, qa, p0, 0, 0, 0);
;         p1 = __builtin_amdgcn_mfma_f32_32x32x16_bf16(a1, qa, p1, 0, 0, 0);
;     }
;     if (MODE == MODE_DIFF) {
;         if (k0 + 63 + 113 > qw0) {
;             LAS const float* rt = dtab + (207 - (qw0 - k0 + r32 - 4 * hi));
; #pragma unroll
;             for (int r = 0; r < 16; ++r) { p0[r] += rt[(r & 3) + 8 * (r >> 2)]; p1[r] += rt[(r & 3) + 8 * (r >> 2) + 32]; }
;     ...
;         float a = fmaxf(fmaxf(p0[0], p0[1]), p1[0]), b = fmaxf(fmaxf(p0[2], p0[3]), p1[1]); a = fmaxf(fmaxf(a, p1[2]), p1[3]);
; #pragma unroll
.LBB0_191:
	ds_read_b128 v[4:7], v222 offset:9216
	ds_read_b128 v[8:11], v222 offset:9248
	s_cmp_le_u32 s51, s46
	s_waitcnt lgkmcnt(1)
	v_mfma_f32_32x32x16_bf16 v[112:127], v[4:7], v[136:139], v[80:95]
	ds_read_b128 v[4:7], v222 offset:13824
	ds_read_b128 v[12:15], v222 offset:13856
	s_waitcnt lgkmcnt(1)
	v_mfma_f32_32x32x16_bf16 v[96:111], v[4:7], v[136:139], v[80:95]
	v_mfma_f32_32x32x16_bf16 v[112:127], v[8:11], v[144:147], v[112:127]
	ds_read_b128 v[4:7], v222 offset:9280
	ds_read_b128 v[8:11], v222 offset:9312
	s_waitcnt lgkmcnt(2)
	v_mfma_f32_32x32x16_bf16 v[96:111], v[12:15], v[144:147], v[96:111]
	s_waitcnt lgkmcnt(1)
	v_mfma_f32_32x32x16_bf16 v[112:127], v[4:7], v[148:151], v[112:127]
	ds_read_b128 v[4:7], v222 offset:13888
	ds_read_b128 v[12:15], v222 offset:13920
	s_waitcnt lgkmcnt(1)
	v_mfma_f32_32x32x16_bf16 v[96:111], v[4:7], v[148:151], v[96:111]
	v_mfma_f32_32x32x16_bf16 v[112:127], v[8:11], v[152:155], v[112:127]
	s_waitcnt lgkmcnt(0)
	v_mfma_f32_32x32x16_bf16 v[96:111], v[12:15], v[152:155], v[96:111]
	s_cbranch_scc1 .LBB0_193
	v_add_u32_e32 v198, s47, v221
	v_add_u32_e32 v0, 0x2243c, v198
	v_add_u32_e32 v4, 0x224bc, v198
	v_add_u32_e32 v6, 0x22444, v198
	v_add_u32_e32 v8, 0x224c4, v198
	v_add_u32_e32 v10, 0x2245c, v198
	v_add_u32_e32 v12, 0x224dc, v198
	v_add_u32_e32 v14, 0x22464, v198
	v_add_u32_e32 v194, 0x224e4, v198
	v_add_u32_e32 v199, 0x2247c, v198
	v_add_u32_e32 v223, 0x224fc, v198
	v_add_u32_e32 v226, 0x22484, v198
	v_add_u32_e32 v228, 0x22504, v198
	ds_read2_b32 v[0:1], v0 offset1:1
	ds_read2_b32 v[4:5], v4 offset1:1
	ds_read2_b32 v[6:7], v6 offset1:1
	ds_read2_b32 v[8:9], v8 offset1:1
	ds_read2_b32 v[10:11], v10 offset1:1
	ds_read2_b32 v[12:13], v12 offset1:1
	ds_read2_b32 v[14:15], v14 offset1:1
	ds_read2_b32 v[194:195], v194 offset1:1
	ds_read2_b32 v[202:203], v199 offset1:1
	ds_read2_b32 v[224:225], v223 offset1:1
	ds_read2_b32 v[226:227], v226 offset1:1
	ds_read2_b32 v[228:229], v228 offset1:1
	v_add_u32_e32 v223, 0x2251c, v198
	v_add_u32_e32 v230, 0x224a4, v198
	v_add_u32_e32 v199, 0x2249c, v198
	ds_read2_b32 v[230:231], v230 offset1:1
	ds_read2_b32 v[232:233], v199 offset1:1
	v_add_u32_e32 v198, 0x22524, v198
	ds_read2_b32 v[234:235], v223 offset1:1
	ds_read2_b32 v[236:237], v198 offset1:1
	s_waitcnt lgkmcnt(5)
	v_add_f32_e32 v122, v122, v226
	v_add_f32_e32 v123, v123, v227
	s_waitcnt lgkmcnt(3)
	v_add_f32_e32 v126, v126, v230
	v_add_f32_e32 v127, v127, v231
	s_waitcnt lgkmcnt(2)
	v_add_f32_e32 v124, v124, v232
	v_add_f32_e32 v125, v125, v233
	v_add_f32_e32 v120, v120, v202
	v_add_f32_e32 v121, v121, v203
	v_add_f32_e32 v118, v118, v14
	v_add_f32_e32 v119, v119, v15
	v_add_f32_e32 v116, v116, v10
	v_add_f32_e32 v117, v117, v11
	v_add_f32_e32 v114, v114, v6
	v_add_f32_e32 v115, v115, v7
	v_add_f32_e32 v112, v112, v0
	v_add_f32_e32 v113, v113, v1
	s_waitcnt lgkmcnt(0)
	v_add_f32_e32 v110, v110, v236
	v_add_f32_e32 v111, v111, v237
	v_add_f32_e32 v108, v108, v234
	v_add_f32_e32 v109, v109, v235
	v_add_f32_e32 v106, v106, v228
	v_add_f32_e32 v107, v107, v229
	v_add_f32_e32 v104, v104, v224
	v_add_f32_e32 v105, v105, v225
	v_add_f32_e32 v102, v102, v194
	v_add_f32_e32 v103, v103, v195
	v_add_f32_e32 v100, v100, v12
	v_add_f32_e32 v101, v101, v13
	v_add_f32_e32 v98, v98, v8
	v_add_f32_e32 v99, v99, v9
	v_add_f32_e32 v96, v96, v4
	v_add_f32_e32 v97, v97, v5
.LBB0_193:
	s_nop 8
	v_max_f32_e32 v0, v113, v113
	v_max_f32_e32 v1, v112, v112
	v_max_f32_e32 v0, v1, v0
	v_max3_f32 v1, v114, v115, v97
	v_max3_f32 v0, v0, v96, v98
	v_max3_f32 v0, v0, v99, v116
	v_max3_f32 v1, v1, v118, v119
	v_max3_f32 v0, v0, v117, v100
	v_max3_f32 v1, v1, v102, v103
	v_max3_f32 v0, v0, v101, v120
	v_max3_f32 v1, v1, v122, v123
	v_max3_f32 v0, v0, v121, v104
	v_max3_f32 v1, v1, v106, v107
	v_max3_f32 v0, v0, v105, v124
	v_max3_f32 v1, v1, v126, v127
	v_max3_f32 v0, v0, v125, v108
	v_max3_f32 v1, v1, v110, v111
	v_max3_f32 v0, v0, v109, v1
	v_mov_b32_e32 v1, v0
	v_mov_b32_e32 v4, v0
	s_nop 1
	v_permlane32_swap_b32_e32 v1, v4
	v_xor_b32_e32 v1, v1, v4
	v_xor_b32_e32 v1, v1, v0
	v_max_f32_e32 v1, v1, v1
	v_max_f32_e32 v0, v0, v1
	v_cmp_lt_f32_e32 vcc, s53, v0
	s_cbranch_vccz .LBB0_197
	v_cmp_lg_f32_e32 vcc, s85, v0
	v_cmp_nge_f32_e64 s[44:45], s53, 0
	s_nop 0
	v_cndmask_b32_e32 v1, 0, v0, vcc
	v_max_f32_e32 v0, v0, v0
	v_max_f32_e32 v0, 0, v0
	v_cmp_lt_f32_e64 vcc, s53, 0
	s_nop 1
	v_cndmask_b32_e32 v0, v0, v1, vcc
	s_and_b64 vcc, exec, s[44:45]
	s_cbranch_vccnz .LBB0_196
	v_exp_f32_e64 v4, -v0
	s_nop 0
	v_mul_f32_e32 v3, v3, v4
	v_mul_f32_e32 v78, v78, v4
	v_mul_f32_e32 v79, v79, v4
	v_mul_f32_e32 v76, v76, v4
	v_mul_f32_e32 v77, v77, v4
	v_mul_f32_e32 v74, v74, v4
	v_mul_f32_e32 v75, v75, v4
	v_mul_f32_e32 v72, v72, v4
	v_mul_f32_e32 v73, v73, v4
	v_mul_f32_e32 v70, v70, v4
	v_mul_f32_e32 v71, v71, v4
	v_mul_f32_e32 v68, v68, v4
	v_mul_f32_e32 v69, v69, v4
	v_mul_f32_e32 v66, v66, v4
	v_mul_f32_e32 v67, v67, v4
	v_mul_f32_e32 v64, v64, v4
	v_mul_f32_e32 v65, v65, v4
	v_mul_f32_e32 v62, v62, v4
	v_mul_f32_e32 v63, v63, v4
	v_mul_f32_e32 v60, v60, v4
	v_mul_f32_e32 v61, v61, v4
	v_mul_f32_e32 v58, v58, v4
	v_mul_f32_e32 v59, v59, v4
	v_mul_f32_e32 v56, v56, v4
	v_mul_f32_e32 v57, v57, v4
	v_mul_f32_e32 v54, v54, v4
	v_mul_f32_e32 v55, v55, v4
	v_mul_f32_e32 v52, v52, v4
	v_mul_f32_e32 v53, v53, v4
	v_mul_f32_e32 v50, v50, v4
	v_mul_f32_e32 v51, v51, v4
	v_mul_f32_e32 v48, v48, v4
	v_mul_f32_e32 v49, v49, v4
	v_mul_f32_e32 v46, v46, v4
	v_mul_f32_e32 v47, v47, v4
	v_mul_f32_e32 v44, v44, v4
	v_mul_f32_e32 v45, v45, v4
	v_mul_f32_e32 v42, v42, v4
	v_mul_f32_e32 v43, v43, v4
	v_mul_f32_e32 v40, v40, v4
	v_mul_f32_e32 v41, v41, v4
	v_mul_f32_e32 v38, v38, v4
	v_mul_f32_e32 v39, v39, v4
	v_mul_f32_e32 v36, v36, v4
	v_mul_f32_e32 v37, v37, v4
	v_mul_f32_e32 v34, v34, v4
	v_mul_f32_e32 v35, v35, v4
	v_mul_f32_e32 v32, v32, v4
	v_mul_f32_e32 v33, v33, v4
	v_mul_f32_e32 v30, v30, v4
	v_mul_f32_e32 v31, v31, v4
	v_mul_f32_e32 v28, v28, v4
	v_mul_f32_e32 v29, v29, v4
	v_mul_f32_e32 v26, v26, v4
	v_mul_f32_e32 v27, v27, v4
	v_mul_f32_e32 v24, v24, v4
	v_mul_f32_e32 v25, v25, v4
	v_mul_f32_e32 v22, v22, v4
	v_mul_f32_e32 v23, v23, v4
	v_mul_f32_e32 v20, v20, v4
	v_mul_f32_e32 v21, v21, v4
	v_mul_f32_e32 v18, v18, v4
	v_mul_f32_e32 v19, v19, v4
	v_mul_f32_e32 v16, v16, v4
	v_mul_f32_e32 v17, v17, v4

; __device__ __forceinline__ unsigned cvtpk(float lo, float hi) { f32x2 v = {lo, hi}; bf16x2_t b = __builtin_convertvector(v, bf16x2_t); return __builtin_bit_cast(unsigned, b); }
; #define LAS __attribute__((address_space(3)))
; template <int MODE, int NDG> ...
;     ...
;         float s0 = 0.f, s1 = 0.f;
; #pragma unroll
;         for (int r = 0; r < 16; ++r) { p0[r] = __builtin_amdgcn_exp2f(p0[r]); p1[r] = __builtin_amdgcn_exp2f(p1[r]); s0 += p0[r]; s1 += p1[r]; }
;         l += s0 + s1;
;         pw[0] = (u32x4){cvtpk(p0[0], p0[1]), cvtpk(p0[2], p0[3]), cvtpk(p0[4], p0[5]), cvtpk(p0[6], p0[7])};
;         pw[1] = (u32x4){cvtpk(p0[8], p0[9]), cvtpk(p0[10], p0[11]), cvtpk(p0[12], p0[13]), cvtpk(p0[14], p0[15])};
;         pw[2] = (u32x4){cvtpk(p1[0], p1[1]), cvtpk(p1[2], p1[3]), cvtpk(p1[4], p1[5]), cvtpk(p1[6], p1[7])};
;         pw[3] = (u32x4){cvtpk(p1[8], p1[9]), cvtpk(p1[10], p1[11]), cvtpk(p1[12], p1[13]), cvtpk(p1[14], p1[15])};
;     }
;     LAS const unsigned char* vp = vst + ((lane >> 4) & 1) * 32 + (lane & 3) * 8 + (4 * hi + ((lane & 15) >> 2)) * 64;
; #pragma unroll
;     for (int ks = 0; ks < 4; ++ks)
; #pragma unroll
;         for (int dg = 0; dg < NDG; ++dg) {
;             const bf16x8 vf = vfrag(vp + dg * 4096 + ks * 1024);
;             o[dg] = __builtin_amdgcn_mfma_f32_32x32x16_bf16(vf, __builtin_bit_cast(bf16x8, pw[ks]), o[dg], 0, 0, 0);
;         }
.LBB0_197:
	v_add3_u32 v0, s54, v212, v181
	v_add3_u32 v194, v0, v213, v214
	v_exp_f32_e32 v1, v112
	v_exp_f32_e32 v5, v113
	v_exp_f32_e32 v7, v114
	v_exp_f32_e32 v9, v115
	v_exp_f32_e32 v11, v116
	v_exp_f32_e32 v13, v117
	ds_read_b64_tr_b16 v[114:115], v194 offset:53248
	ds_read_b64_tr_b16 v[116:117], v194 offset:53760
	v_exp_f32_e32 v113, v118
	v_exp_f32_e32 v15, v119
	v_cvt_pk_bf16_f32 v224, v1, v5
	v_cvt_pk_bf16_f32 v225, v7, v9
	v_cvt_pk_bf16_f32 v226, v11, v13
	v_cvt_pk_bf16_f32 v227, v113, v15
	ds_read_b64_tr_b16 v[228:229], v194 offset:54272
	ds_read_b64_tr_b16 v[230:231], v194 offset:54784
	s_waitcnt lgkmcnt(2)
	v_mfma_f32_32x32x16_bf16 v[64:79], v[114:117], v[224:227], v[64:79]
	ds_read_b64_tr_b16 v[114:115], v194 offset:57344
	ds_read_b64_tr_b16 v[116:117], v194 offset:57856
	ds_read_b64_tr_b16 v[232:233], v194 offset:58368
	ds_read_b64_tr_b16 v[234:235], v194 offset:58880
	v_add_u32_e32 v198, 0xd000, v194
	v_exp_f32_e32 v195, v120
	v_exp_f32_e32 v121, v121
	v_exp_f32_e32 v119, v122
	v_exp_f32_e32 v203, v125
	v_exp_f32_e32 v125, v126
	s_waitcnt lgkmcnt(2)
	v_mfma_f32_32x32x16_bf16 v[48:63], v[114:117], v[224:227], v[48:63]
	ds_read_b64_tr_b16 v[114:115], v194 offset:61440
	ds_read_b64_tr_b16 v[116:117], v194 offset:61952
	ds_read_b64_tr_b16 v[236:237], v198 offset:12288
	ds_read_b64_tr_b16 v[238:239], v198 offset:12800
	ds_read_b64_tr_b16 v[240:241], v194 offset:62464
	ds_read_b64_tr_b16 v[242:243], v194 offset:62976
	ds_read_b64_tr_b16 v[244:245], v198 offset:13312
	ds_read_b64_tr_b16 v[246:247], v198 offset:13824
	v_exp_f32_e32 v0, v96
	v_exp_f32_e32 v4, v97
	v_exp_f32_e32 v6, v98
	v_exp_f32_e32 v8, v99
	s_waitcnt lgkmcnt(6)
	v_mfma_f32_32x32x16_bf16 v[32:47], v[114:117], v[224:227], v[32:47]
	v_exp_f32_e32 v117, v123
	v_exp_f32_e32 v115, v124
	v_exp_f32_e32 v123, v127
	v_exp_f32_e32 v10, v100
	v_exp_f32_e32 v12, v101
	v_exp_f32_e32 v112, v102
	ds_read_b64_tr_b16 v[96:97], v194 offset:55296
	ds_read_b64_tr_b16 v[98:99], v194 offset:55808
	s_waitcnt lgkmcnt(6)
	v_mfma_f32_32x32x16_bf16 v[16:31], v[236:239], v[224:227], v[16:31]
	v_cvt_pk_bf16_f32 v224, v195, v121
	v_cvt_pk_bf16_f32 v225, v119, v117
	v_cvt_pk_bf16_f32 v226, v115, v203
	v_cvt_pk_bf16_f32 v227, v125, v123
	v_exp_f32_e32 v14, v103
	v_cvt_pk_bf16_f32 v100, v0, v4
	v_cvt_pk_bf16_f32 v101, v6, v8
	v_mfma_f32_32x32x16_bf16 v[64:79], v[228:231], v[224:227], v[64:79]
	v_cvt_pk_bf16_f32 v102, v10, v12
	v_cvt_pk_bf16_f32 v103, v112, v14
	v_add_f32_e64 v0, v0, 0
	v_add_f32_e64 v1, v1, 0
	v_exp_f32_e32 v120, v105
	v_add_f32_e32 v0, v4, v0
	v_add_f32_e32 v1, v5, v1
	v_exp_f32_e32 v118, v106
	v_add_f32_e32 v0, v6, v0
	v_add_f32_e32 v1, v7, v1
	v_mfma_f32_32x32x16_bf16 v[48:63], v[232:235], v[224:227], v[48:63]
	v_add_f32_e64 v0, v8, v0
	v_add_f32_e64 v1, v9, v1
	v_exp_f32_e32 v116, v107
	v_add_f32_e32 v0, v10, v0
	v_add_f32_e32 v1, v11, v1
	v_exp_f32_e32 v114, v108
	v_exp_f32_e32 v202, v109
	v_exp_f32_e32 v124, v110
	v_exp_f32_e32 v122, v111
	s_waitcnt lgkmcnt(4)
	v_mfma_f32_32x32x16_bf16 v[32:47], v[240:243], v[224:227], v[32:47]
	v_add_f32_e64 v0, v12, v0
	v_add_f32_e64 v1, v13, v1
	v_add_f32_e64 v0, v112, v0
	v_add_f32_e64 v1, v113, v1
	v_add_f32_e64 v0, v14, v0
	v_add_f32_e64 v1, v15, v1
	s_waitcnt lgkmcnt(2)
	v_mfma_f32_32x32x16_bf16 v[16:31], v[244:247], v[224:227], v[16:31]
	ds_read_b64_tr_b16 v[224:225], v194 offset:56320
	ds_read_b64_tr_b16 v[226:227], v194 offset:56832
	s_waitcnt lgkmcnt(2)
	v_mfma_f32_32x32x16_bf16 v[64:79], v[96:99], v[100:103], v[64:79]
	ds_read_b64_tr_b16 v[96:97], v194 offset:59392
	ds_read_b64_tr_b16 v[98:99], v194 offset:59904
	ds_read_b64_tr_b16 v[228:229], v194 offset:60416
	ds_read_b64_tr_b16 v[230:231], v194 offset:60928
	s_waitcnt lgkmcnt(2)
	v_mfma_f32_32x32x16_bf16 v[48:63], v[96:99], v[100:103], v[48:63]
	ds_read_b64_tr_b16 v[96:97], v194 offset:63488
	ds_read_b64_tr_b16 v[98:99], v194 offset:64000
	ds_read_b64_tr_b16 v[232:233], v198 offset:14336
	ds_read_b64_tr_b16 v[234:235], v198 offset:14848
	ds_read_b64_tr_b16 v[236:237], v194 offset:64512
	ds_read_b64_tr_b16 v[238:239], v194 offset:65024
	v_exp_f32_e32 v194, v104
	s_nop 0
	v_add_f32_e32 v0, v194, v0
	v_add_f32_e32 v1, v195, v1
	s_nop 0
	v_add_f32_e32 v0, v120, v0
	v_add_f32_e32 v1, v121, v1
	s_waitcnt lgkmcnt(4)
	v_mfma_f32_32x32x16_bf16 v[32:47], v[96:99], v[100:103], v[32:47]
	ds_read_b64_tr_b16 v[96:97], v198 offset:15360
	ds_read_b64_tr_b16 v[98:99], v198 offset:15872
	v_add_f32_e64 v0, v118, v0
	v_add_f32_e64 v1, v119, v1
	v_add_f32_e64 v0, v116, v0
	v_add_f32_e64 v1, v117, v1
	v_add_f32_e32 v0, v114, v0
	v_add_f32_e32 v1, v115, v1
	s_waitcnt lgkmcnt(4)
	v_mfma_f32_32x32x16_bf16 v[16:31], v[232:235], v[100:103], v[16:31]
	v_cvt_pk_bf16_f32 v100, v194, v120
	v_cvt_pk_bf16_f32 v101, v118, v116
	v_cvt_pk_bf16_f32 v102, v114, v202
	v_cvt_pk_bf16_f32 v103, v124, v122
	v_add_f32_e64 v0, v202, v0
	v_add_f32_e64 v1, v203, v1
	v_add_f32_e32 v0, v124, v0
	v_add_f32_e32 v1, v125, v1
	v_mfma_f32_32x32x16_bf16 v[64:79], v[224:227], v[100:103], v[64:79]
	v_add_f32_e64 v0, v122, v0
	v_add_f32_e64 v1, v123, v1
	v_add_f32_e32 v0, v0, v1
	v_add_f32_e32 v3, v3, v0
	v_mfma_f32_32x32x16_bf16 v[48:63], v[228:231], v[100:103], v[48:63]
	s_waitcnt lgkmcnt(2)
	v_mfma_f32_32x32x16_bf16 v[32:47], v[236:239], v[100:103], v[32:47]
	s_waitcnt lgkmcnt(0)
	v_mfma_f32_32x32x16_bf16 v[16:31], v[96:99], v[100:103], v[16:31]
	s_cmp_gt_u32 s50, s48
	s_cbranch_scc1 .LBB0_190
; #define LAS __attribute__((address_space(3)))
; template <int MODE, int NDG> ...
;     ...
;         const bf16x8 a0 = lds16(kp), a1 = lds16(kp + 32 * 144);
;         p0 = __builtin_amdgcn_mfma_f32_32x32x16_bf16(a0, qr[0], MODE == MODE_SB ? z : negm, 0, 0, 0);
;         p1 = __builtin_amdgcn_mfma_f32_32x32x16_bf16(a1, qr[0], MODE == MODE_SB ? z : negm, 0, 0, 0); }
; #pragma unroll
;     for (int d0 = 1; d0 < 4; ++d0) {
;         const bf16x8 a0 = lds16(kp + d0 * 32), a1 = lds16(kp + 32 * 144 + d0 * 32);
;         p0 = __builtin_amdgcn_mfma_f32_32x32x16_bf16(a0, qr[d0], p0, 0, 0, 0);
;         p1 = __builtin_amdgcn_mfma_f32_32x32x16_bf16(a1, qr[d0], p1, 0, 0, 0);
;     }
;     ...
;     if (MODE == MODE_DIFF) { f32x16 d0_ = p0, d1_ = p1;
; #pragma unroll
;         for (int d0 = 0; d0 < 4; ++d0) { d0_ = __builtin_amdgcn_mfma_f32_32x32x16_bf16(qr[d0], qr[d0], d0_, 0, 0, 0); d1_ = __builtin_amdgcn_mfma_f32_32x32x16_bf16(qr[d0], qr[d0], d1_, 0, 0, 0); }
;         asm volatile("" :: "v"(d0_), "v"(d1_)); }
;     ...
;     if (MODE == MODE_DIFF) {
; #pragma unroll
;         for (int d0 = 0; d0 < 4; ++d0) { const bf16x8 a0 = lds16(kp + d0 * 32 + 64 * 144), a1 = lds16(kp + 32 * 144 + d0 * 32 + 64 * 144); asm volatile("" :: "v"(a0), "v"(a1)); }
;         LAS const unsigned char* vq = vst + ((lane >> 4) & 1) * 32 + (lane & 3) * 8 + (4 * hi + ((lane & 15) >> 2)) * 64;
; #pragma unroll
;         for (int i = 0; i < 8; ++i) { const bf16x8 vf = vfrag(vq + i * 1024); asm volatile("" :: "v"(vf)); } }
;     ...
;     if (MODE == MODE_FOX) {
;         const bf16x8 a0 = lds16(ast + r32 * 16), a1 = lds16(ast + (32 + r32) * 16);
;         const short one = hi ? (short)0 : (short)0x3F80;
;         const bf16x8 qa = (bf16x8){one, one, one, 0, 0, 0, 0, 0};
;         p0 = __builtin_amdgcn_mfma_f32_32x32x16_bf16(a0, qa, p0, 0, 0, 0);
;         p1 = __builtin_amdgcn_mfma_f32_32x32x16_bf16(a1, qa, p1, 0, 0, 0);
;     }
;     if (MODE == MODE_DIFF) {
;         if (k0 + 63 + 113 > qw0) {
;             LAS const float* rt = dtab + (207 - (qw0 - k0 + r32 - 4 * hi));
; #pragma unroll
;             for (int r = 0; r < 16; ++r) { p0[r] += rt[(r & 3) + 8 * (r >> 2)]; p1[r] += rt[(r & 3) + 8 * (r >> 2) + 32]; }
;         }
.LBB0_198:
	ds_read_b128 v[4:7], v222
	ds_read_b128 v[8:11], v222 offset:32
	s_sub_i32 s3, s51, 64
	s_cmp_le_u32 s3, s46
	s_waitcnt lgkmcnt(1)
	v_mfma_f32_32x32x16_bf16 v[112:127], v[4:7], v[136:139], v[80:95]
	ds_read_b128 v[4:7], v222 offset:4608
	ds_read_b128 v[12:15], v222 offset:4640
	s_waitcnt lgkmcnt(1)
	v_mfma_f32_32x32x16_bf16 v[96:111], v[4:7], v[136:139], v[80:95]
	v_mfma_f32_32x32x16_bf16 v[112:127], v[8:11], v[144:147], v[112:127]
	ds_read_b128 v[4:7], v222 offset:64
	ds_read_b128 v[8:11], v222 offset:96
	s_waitcnt lgkmcnt(2)
	v_mfma_f32_32x32x16_bf16 v[96:111], v[12:15], v[144:147], v[96:111]
	s_waitcnt lgkmcnt(1)
	v_mfma_f32_32x32x16_bf16 v[112:127], v[4:7], v[148:151], v[112:127]
	ds_read_b128 v[4:7], v222 offset:4672
	ds_read_b128 v[12:15], v222 offset:4704
	s_waitcnt lgkmcnt(1)
	v_mfma_f32_32x32x16_bf16 v[96:111], v[4:7], v[148:151], v[96:111]
	v_mfma_f32_32x32x16_bf16 v[112:127], v[8:11], v[152:155], v[112:127]
	s_waitcnt lgkmcnt(0)
	v_mfma_f32_32x32x16_bf16 v[96:111], v[12:15], v[152:155], v[96:111]
	s_cbranch_scc1 .LBB0_200
	v_add_u32_e32 v198, s47, v221
	v_add_u32_e32 v0, 0x2233c, v198
	v_add_u32_e32 v4, 0x223bc, v198
	v_add_u32_e32 v6, 0x22344, v198
	v_add_u32_e32 v8, 0x223c4, v198
	v_add_u32_e32 v10, 0x2235c, v198
	v_add_u32_e32 v12, 0x223dc, v198
	v_add_u32_e32 v14, 0x22364, v198
	v_add_u32_e32 v194, 0x223e4, v198
	v_add_u32_e32 v199, 0x2237c, v198
	v_add_u32_e32 v222, 0x223fc, v198
	v_add_u32_e32 v224, 0x22384, v198
	v_add_u32_e32 v226, 0x22404, v198
	v_add_u32_e32 v232, 0x2241c, v198
	v_add_u32_e32 v228, 0x223a4, v198
	ds_read2_b32 v[0:1], v0 offset1:1
	ds_read2_b32 v[4:5], v4 offset1:1
	ds_read2_b32 v[6:7], v6 offset1:1
	ds_read2_b32 v[8:9], v8 offset1:1
	ds_read2_b32 v[10:11], v10 offset1:1
	ds_read2_b32 v[12:13], v12 offset1:1
	ds_read2_b32 v[14:15], v14 offset1:1
	ds_read2_b32 v[194:195], v194 offset1:1
	ds_read2_b32 v[202:203], v199 offset1:1
	ds_read2_b32 v[222:223], v222 offset1:1
	ds_read2_b32 v[224:225], v224 offset1:1
	ds_read2_b32 v[226:227], v226 offset1:1
	v_add_u32_e32 v199, 0x2239c, v198
	ds_read2_b32 v[228:229], v228 offset1:1
	ds_read2_b32 v[230:231], v199 offset1:1
	v_add_u32_e32 v198, 0x22424, v198
	ds_read2_b32 v[232:233], v232 offset1:1
	ds_read2_b32 v[234:235], v198 offset1:1
	s_waitcnt lgkmcnt(5)
	v_add_f32_e32 v122, v122, v224
	v_add_f32_e32 v123, v123, v225
	s_waitcnt lgkmcnt(3)
	v_add_f32_e32 v126, v126, v228
	v_add_f32_e32 v127, v127, v229
	s_waitcnt lgkmcnt(2)
	v_add_f32_e32 v124, v124, v230
	v_add_f32_e32 v125, v125, v231
	v_add_f32_e32 v120, v120, v202
	v_add_f32_e32 v121, v121, v203
	v_add_f32_e32 v118, v118, v14
	v_add_f32_e32 v119, v119, v15
	v_add_f32_e32 v116, v116, v10
	v_add_f32_e32 v117, v117, v11
	v_add_f32_e32 v114, v114, v6
	v_add_f32_e32 v115, v115, v7
	v_add_f32_e32 v112, v112, v0
	v_add_f32_e32 v113, v113, v1
	s_waitcnt lgkmcnt(0)
	v_add_f32_e32 v110, v110, v234
	v_add_f32_e32 v111, v111, v235
	v_add_f32_e32 v108, v108, v232
	v_add_f32_e32 v109, v109, v233
	v_add_f32_e32 v106, v106, v226
	v_add_f32_e32 v107, v107, v227
	v_add_f32_e32 v104, v104, v222
	v_add_f32_e32 v105, v105, v223
	v_add_f32_e32 v102, v102, v194
	v_add_f32_e32 v103, v103, v195
	v_add_f32_e32 v100, v100, v12
	v_add_f32_e32 v101, v101, v13
	v_add_f32_e32 v98, v98, v8
	v_add_f32_e32 v99, v99, v9
	v_add_f32_e32 v96, v96, v4
	v_add_f32_e32 v97, v97, v5

; __device__ __forceinline__ unsigned cvtpk(float lo, float hi) { f32x2 v = {lo, hi}; bf16x2_t b = __builtin_convertvector(v, bf16x2_t); return __builtin_bit_cast(unsigned, b); }
; #define LAS __attribute__((address_space(3)))
; template <int MODE, int NDG> ...
;     ...
;         float s0 = 0.f, s1 = 0.f;
; #pragma unroll
;         for (int r = 0; r < 16; ++r) { p0[r] = __builtin_amdgcn_exp2f(p0[r]); p1[r] = __builtin_amdgcn_exp2f(p1[r]); s0 += p0[r]; s1 += p1[r]; }
;         l += s0 + s1;
;         pw[0] = (u32x4){cvtpk(p0[0], p0[1]), cvtpk(p0[2], p0[3]), cvtpk(p0[4], p0[5]), cvtpk(p0[6], p0[7])};
;         pw[1] = (u32x4){cvtpk(p0[8], p0[9]), cvtpk(p0[10], p0[11]), cvtpk(p0[12], p0[13]), cvtpk(p0[14], p0[15])};
;         pw[2] = (u32x4){cvtpk(p1[0], p1[1]), cvtpk(p1[2], p1[3]), cvtpk(p1[4], p1[5]), cvtpk(p1[6], p1[7])};
;         pw[3] = (u32x4){cvtpk(p1[8], p1[9]), cvtpk(p1[10], p1[11]), cvtpk(p1[12], p1[13]), cvtpk(p1[14], p1[15])};
;     }
;     LAS const unsigned char* vp = vst + ((lane >> 4) & 1) * 32 + (lane & 3) * 8 + (4 * hi + ((lane & 15) >> 2)) * 64;
; #pragma unroll
;     for (int ks = 0; ks < 4; ++ks)
; #pragma unroll
;         for (int dg = 0; dg < NDG; ++dg) {
;             const bf16x8 vf = vfrag(vp + dg * 4096 + ks * 1024);
;             o[dg] = __builtin_amdgcn_mfma_f32_32x32x16_bf16(vf, __builtin_bit_cast(bf16x8, pw[ks]), o[dg], 0, 0, 0);
;         }
.LBB0_204:
	v_add3_u32 v0, s54, v212, v181
	v_add3_u32 v198, v0, v213, v214
	v_exp_f32_e32 v1, v112
	v_exp_f32_e32 v5, v113
	v_exp_f32_e32 v7, v114
	v_exp_f32_e32 v9, v115
	v_exp_f32_e32 v11, v116
	v_exp_f32_e32 v13, v117
	ds_read_b64_tr_b16 v[114:115], v198 offset:36864
	ds_read_b64_tr_b16 v[116:117], v198 offset:37376
	v_exp_f32_e32 v113, v118
	v_exp_f32_e32 v15, v119
	v_cvt_pk_bf16_f32 v222, v1, v5
	v_cvt_pk_bf16_f32 v223, v7, v9
	v_cvt_pk_bf16_f32 v224, v11, v13
	v_cvt_pk_bf16_f32 v225, v113, v15
	ds_read_b64_tr_b16 v[226:227], v198 offset:37888
	ds_read_b64_tr_b16 v[228:229], v198 offset:38400
	s_waitcnt lgkmcnt(2)
	v_mfma_f32_32x32x16_bf16 v[64:79], v[114:117], v[222:225], v[64:79]
	ds_read_b64_tr_b16 v[114:115], v198 offset:40960
	ds_read_b64_tr_b16 v[116:117], v198 offset:41472
	ds_read_b64_tr_b16 v[230:231], v198 offset:41984
	ds_read_b64_tr_b16 v[232:233], v198 offset:42496
	v_exp_f32_e32 v195, v120
	v_exp_f32_e32 v121, v121
	v_exp_f32_e32 v119, v122
	v_exp_f32_e32 v203, v125
	v_exp_f32_e32 v125, v126
	v_exp_f32_e32 v0, v96
	s_waitcnt lgkmcnt(2)
	v_mfma_f32_32x32x16_bf16 v[48:63], v[114:117], v[222:225], v[48:63]
	ds_read_b64_tr_b16 v[114:115], v198 offset:45056
	ds_read_b64_tr_b16 v[116:117], v198 offset:45568
	ds_read_b64_tr_b16 v[234:235], v198 offset:49152
	ds_read_b64_tr_b16 v[236:237], v198 offset:49664
	ds_read_b64_tr_b16 v[238:239], v198 offset:46080
	ds_read_b64_tr_b16 v[240:241], v198 offset:46592
	ds_read_b64_tr_b16 v[242:243], v198 offset:50176
	ds_read_b64_tr_b16 v[244:245], v198 offset:50688
	v_exp_f32_e32 v4, v97
	v_exp_f32_e32 v6, v98
	v_exp_f32_e32 v8, v99
	v_exp_f32_e32 v10, v100
	v_exp_f32_e32 v12, v101
	s_waitcnt lgkmcnt(6)
	v_mfma_f32_32x32x16_bf16 v[32:47], v[114:117], v[222:225], v[32:47]
	v_exp_f32_e32 v117, v123
	v_exp_f32_e32 v115, v124
	v_exp_f32_e32 v123, v127
	v_exp_f32_e32 v112, v102
	ds_read_b64_tr_b16 v[96:97], v198 offset:38912
	ds_read_b64_tr_b16 v[98:99], v198 offset:39424
	v_exp_f32_e32 v14, v103
	v_cvt_pk_bf16_f32 v100, v0, v4
	s_waitcnt lgkmcnt(6)
	v_mfma_f32_32x32x16_bf16 v[16:31], v[234:237], v[222:225], v[16:31]
	v_cvt_pk_bf16_f32 v222, v195, v121
	v_cvt_pk_bf16_f32 v223, v119, v117
	v_cvt_pk_bf16_f32 v224, v115, v203
	v_cvt_pk_bf16_f32 v225, v125, v123
	v_cvt_pk_bf16_f32 v101, v6, v8
	v_cvt_pk_bf16_f32 v102, v10, v12
	v_cvt_pk_bf16_f32 v103, v112, v14
	v_mfma_f32_32x32x16_bf16 v[64:79], v[226:229], v[222:225], v[64:79]
	v_add_f32_e64 v0, v0, 0
	v_add_f32_e64 v1, v1, 0
	v_exp_f32_e32 v194, v104
	v_add_f32_e32 v0, v4, v0
	v_add_f32_e32 v1, v5, v1
	v_exp_f32_e32 v120, v105
	v_add_f32_e32 v0, v6, v0
	v_add_f32_e32 v1, v7, v1
	v_exp_f32_e32 v118, v106
	v_add_f32_e32 v0, v8, v0
	v_add_f32_e32 v1, v9, v1
	v_mfma_f32_32x32x16_bf16 v[48:63], v[230:233], v[222:225], v[48:63]
	v_add_f32_e64 v0, v10, v0
	v_add_f32_e64 v1, v11, v1
	v_exp_f32_e32 v116, v107
	v_exp_f32_e32 v114, v108
	v_exp_f32_e32 v202, v109
	v_exp_f32_e32 v124, v110
	v_exp_f32_e32 v122, v111
	v_add_f32_e32 v0, v12, v0
	v_add_f32_e32 v1, v13, v1
	s_waitcnt lgkmcnt(4)
	v_mfma_f32_32x32x16_bf16 v[32:47], v[238:241], v[222:225], v[32:47]
	v_add_f32_e64 v0, v112, v0
	v_add_f32_e64 v1, v113, v1
	v_add_f32_e64 v0, v14, v0
	v_add_f32_e64 v1, v15, v1
	v_add_f32_e64 v0, v194, v0
	v_add_f32_e64 v1, v195, v1
	v_add_f32_e32 v0, v120, v0
	v_add_f32_e32 v1, v121, v1
	s_waitcnt lgkmcnt(2)
	v_mfma_f32_32x32x16_bf16 v[16:31], v[242:245], v[222:225], v[16:31]
	ds_read_b64_tr_b16 v[222:223], v198 offset:39936
	ds_read_b64_tr_b16 v[224:225], v198 offset:40448
	v_add_f32_e64 v0, v118, v0
	v_add_f32_e64 v1, v119, v1
	v_add_f32_e64 v0, v116, v0
	v_add_f32_e64 v1, v117, v1
	v_add_f32_e32 v0, v114, v0
	v_add_f32_e32 v1, v115, v1
	s_waitcnt lgkmcnt(2)
	v_mfma_f32_32x32x16_bf16 v[64:79], v[96:99], v[100:103], v[64:79]
	ds_read_b64_tr_b16 v[96:97], v198 offset:43008
	ds_read_b64_tr_b16 v[98:99], v198 offset:43520
	ds_read_b64_tr_b16 v[226:227], v198 offset:44032
	ds_read_b64_tr_b16 v[228:229], v198 offset:44544
	v_add_f32_e64 v0, v202, v0
	v_add_f32_e64 v1, v203, v1
	v_add_f32_e32 v0, v124, v0
	v_add_f32_e32 v1, v125, v1
	s_nop 0
	v_add_f32_e32 v0, v122, v0
	v_add_f32_e32 v1, v123, v1
	s_waitcnt lgkmcnt(2)
	v_mfma_f32_32x32x16_bf16 v[48:63], v[96:99], v[100:103], v[48:63]
	ds_read_b64_tr_b16 v[96:97], v198 offset:47104
	ds_read_b64_tr_b16 v[98:99], v198 offset:47616
	ds_read_b64_tr_b16 v[230:231], v198 offset:51200
	ds_read_b64_tr_b16 v[232:233], v198 offset:51712
	ds_read_b64_tr_b16 v[234:235], v198 offset:48128
	ds_read_b64_tr_b16 v[236:237], v198 offset:48640
	v_add_f32_e32 v0, v0, v1
	v_add_f32_e32 v3, v3, v0
	s_waitcnt lgkmcnt(4)
	v_mfma_f32_32x32x16_bf16 v[32:47], v[96:99], v[100:103], v[32:47]
	ds_read_b64_tr_b16 v[96:97], v198 offset:52224
	ds_read_b64_tr_b16 v[98:99], v198 offset:52736
	s_waitcnt lgkmcnt(4)
	v_mfma_f32_32x32x16_bf16 v[16:31], v[230:233], v[100:103], v[16:31]
	v_cvt_pk_bf16_f32 v100, v194, v120
	v_cvt_pk_bf16_f32 v101, v118, v116
	v_cvt_pk_bf16_f32 v102, v114, v202
	v_cvt_pk_bf16_f32 v103, v124, v122
	s_nop 1
	v_mfma_f32_32x32x16_bf16 v[64:79], v[222:225], v[100:103], v[64:79]
	v_mfma_f32_32x32x16_bf16 v[48:63], v[226:229], v[100:103], v[48:63]
	s_waitcnt lgkmcnt(2)
	v_mfma_f32_32x32x16_bf16 v[32:47], v[234:237], v[100:103], v[32:47]
	s_waitcnt lgkmcnt(0)
	v_mfma_f32_32x32x16_bf16 v[16:31], v[96:99], v[100:103], v[16:31]
	s_andn2_b64 vcc, exec, s[30:31]
	s_add_i32 s52, s52, 1
	s_cbranch_vccnz .LBB0_185

; template <int MODE, int NDG> ...
;     ...
;         float a = fmaxf(fmaxf(p0[0], p0[1]), p1[0]), b = fmaxf(fmaxf(p0[2], p0[3]), p1[1]); a = fmaxf(fmaxf(a, p1[2]), p1[3]);
; #pragma unroll
;         for (int r = 4; r < 16; r += 4) { a = fmaxf(fmaxf(a, p0[r]), p0[r + 1]); b = fmaxf(fmaxf(b, p0[r + 2]), p0[r + 3]); a = fmaxf(fmaxf(a, p1[r]), p1[r + 1]); b = fmaxf(fmaxf(b, p1[r + 2]), p1[r + 3]); }
;         float rm = fmaxf(a, b); rm = fmaxf(rm, xlane_partner(rm));
;         if (__any(rm > thr)) {
;             const float d = (thr < 0.f) ? ((rm > -INFINITY) ? rm : 0.f) : fmaxf(rm, 0.f);
;             m += d;
; #pragma unroll
;             for (int r = 0; r < 16; ++r) { p0[r] -= d; p1[r] -= d; }
;             if (thr >= 0.f) { const float f = __builtin_amdgcn_exp2f(-d); l *= f;
; #pragma unroll
;                 for (int dg = 0; dg < NDG; ++dg)
; #pragma unroll
;                     for (int r = 0; r < 16; ++r) o[dg][r] *= f; }
.LBB0_236:
	s_nop 8
	v_max_f32_e32 v0, v81, v81
	v_max_f32_e32 v1, v80, v80
	v_max_f32_e32 v0, v1, v0
	v_max3_f32 v1, v82, v83, v65
	v_max3_f32 v0, v0, v64, v66
	v_max3_f32 v0, v0, v67, v84
	v_max3_f32 v1, v1, v86, v87
	v_max3_f32 v0, v0, v85, v68
	v_max3_f32 v1, v1, v70, v71
	v_max3_f32 v0, v0, v69, v88
	v_max3_f32 v1, v1, v90, v91
	v_max3_f32 v0, v0, v89, v72
	v_max3_f32 v1, v1, v74, v75
	v_max3_f32 v0, v0, v73, v92
	v_max3_f32 v1, v1, v94, v95
	v_max3_f32 v0, v0, v93, v76
	v_max3_f32 v1, v1, v78, v79
	v_max3_f32 v0, v0, v77, v1
	v_mov_b32_e32 v1, v0
	v_mov_b32_e32 v4, v0
	s_nop 1
	v_permlane32_swap_b32_e32 v1, v4
	v_xor_b32_e32 v1, v1, v4
	v_xor_b32_e32 v1, v1, v0
	v_max_f32_e32 v1, v1, v1
	v_max_f32_e32 v0, v0, v1
	v_cmp_lt_f32_e32 vcc, s46, v0
	s_cbranch_vccz .LBB0_240
	v_cmp_lg_f32_e32 vcc, s85, v0
	v_cmp_nge_f32_e64 s[44:45], s46, 0
	s_nop 0
	v_cndmask_b32_e32 v1, 0, v0, vcc
	v_max_f32_e32 v0, v0, v0
	v_max_f32_e32 v0, 0, v0
	v_cmp_lt_f32_e64 vcc, s46, 0
	s_nop 1
	v_cndmask_b32_e32 v0, v0, v1, vcc
	s_and_b64 vcc, exec, s[44:45]
	s_cbranch_vccnz .LBB0_239
	v_exp_f32_e64 v4, -v0
	s_nop 0
	v_mul_f32_e32 v184, v184, v4
	v_mul_f32_e32 v46, v46, v4
	v_mul_f32_e32 v47, v47, v4
	v_mul_f32_e32 v44, v44, v4
	v_mul_f32_e32 v45, v45, v4
	v_mul_f32_e32 v42, v42, v4
	v_mul_f32_e32 v43, v43, v4
	v_mul_f32_e32 v40, v40, v4
	v_mul_f32_e32 v41, v41, v4
	v_mul_f32_e32 v38, v38, v4
	v_mul_f32_e32 v39, v39, v4
	v_mul_f32_e32 v36, v36, v4
	v_mul_f32_e32 v37, v37, v4
	v_mul_f32_e32 v34, v34, v4
	v_mul_f32_e32 v35, v35, v4
	v_mul_f32_e32 v32, v32, v4
	v_mul_f32_e32 v33, v33, v4
	v_mul_f32_e32 v30, v30, v4
	v_mul_f32_e32 v31, v31, v4
	v_mul_f32_e32 v28, v28, v4
	v_mul_f32_e32 v29, v29, v4
	v_mul_f32_e32 v26, v26, v4
	v_mul_f32_e32 v27, v27, v4
	v_mul_f32_e32 v24, v24, v4
	v_mul_f32_e32 v25, v25, v4
	v_mul_f32_e32 v22, v22, v4
	v_mul_f32_e32 v23, v23, v4
	v_mul_f32_e32 v20, v20, v4
	v_mul_f32_e32 v21, v21, v4
	v_mul_f32_e32 v18, v18, v4
	v_mul_f32_e32 v19, v19, v4
	v_mul_f32_e32 v16, v16, v4
	v_mul_f32_e32 v17, v17, v4

; __device__ __forceinline__ unsigned cvtpk(float lo, float hi) { f32x2 v = {lo, hi}; bf16x2_t b = __builtin_convertvector(v, bf16x2_t); return __builtin_bit_cast(unsigned, b); }
; #define LAS __attribute__((address_space(3)))
; template <int MODE, int NDG> ...
;     ...
;         float s0 = 0.f, s1 = 0.f;
; #pragma unroll
;         for (int r = 0; r < 16; ++r) { p0[r] = __builtin_amdgcn_exp2f(p0[r]); p1[r] = __builtin_amdgcn_exp2f(p1[r]); s0 += p0[r]; s1 += p1[r]; }
;         l += s0 + s1;
;         pw[0] = (u32x4){cvtpk(p0[0], p0[1]), cvtpk(p0[2], p0[3]), cvtpk(p0[4], p0[5]), cvtpk(p0[6], p0[7])};
;         pw[1] = (u32x4){cvtpk(p0[8], p0[9]), cvtpk(p0[10], p0[11]), cvtpk(p0[12], p0[13]), cvtpk(p0[14], p0[15])};
;         pw[2] = (u32x4){cvtpk(p1[0], p1[1]), cvtpk(p1[2], p1[3]), cvtpk(p1[4], p1[5]), cvtpk(p1[6], p1[7])};
;         pw[3] = (u32x4){cvtpk(p1[8], p1[9]), cvtpk(p1[10], p1[11]), cvtpk(p1[12], p1[13]), cvtpk(p1[14], p1[15])};
;     }
;     LAS const unsigned char* vp = vst + ((lane >> 4) & 1) * 32 + (lane & 3) * 8 + (4 * hi + ((lane & 15) >> 2)) * 64;
; #pragma unroll
;     for (int ks = 0; ks < 4; ++ks)
; #pragma unroll
;         for (int dg = 0; dg < NDG; ++dg) {
;             const bf16x8 vf = vfrag(vp + dg * 4096 + ks * 1024);
;             o[dg] = __builtin_amdgcn_mfma_f32_32x32x16_bf16(vf, __builtin_bit_cast(bf16x8, pw[ks]), o[dg], 0, 0, 0);
;         }
.LBB0_240:
	v_exp_f32_e32 v163, v80
	v_exp_f32_e32 v162, v64
	v_exp_f32_e32 v165, v81
	v_exp_f32_e32 v164, v65
	v_exp_f32_e32 v65, v82
	v_exp_f32_e32 v64, v66
	v_exp_f32_e32 v81, v83
	v_exp_f32_e32 v80, v67
	v_add3_u32 v4, s24, v172, v137
	v_pk_add_f32 v[0:1], v[162:163], 0 op_sel_hi:[1,0]
	v_add3_u32 v194, v4, v173, v174
	v_add_f32_e32 v0, v164, v0
	v_add_f32_e32 v1, v165, v1
	v_exp_f32_e32 v9, v84
	v_exp_f32_e32 v8, v68
	v_exp_f32_e32 v11, v85
	v_exp_f32_e32 v10, v69
	v_exp_f32_e32 v13, v86
	v_exp_f32_e32 v15, v87
	ds_read_b64_tr_b16 v[66:67], v194 offset:26624
	ds_read_b64_tr_b16 v[68:69], v194 offset:27136
	v_add_f32_e32 v0, v64, v0
	v_add_f32_e32 v1, v65, v1
	v_exp_f32_e32 v5, v89
	v_add_f32_e32 v6, v80, v0
	v_add_f32_e32 v7, v81, v1
	v_exp_f32_e32 v1, v88
	ds_read_b64_tr_b16 v[86:87], v194 offset:30720
	ds_read_b64_tr_b16 v[88:89], v194 offset:31232
	ds_read_b64_tr_b16 v[186:187], v194 offset:27648
	ds_read_b64_tr_b16 v[188:189], v194 offset:28160
	v_cvt_pk_bf16_f32 v82, v163, v165
	v_cvt_pk_bf16_f32 v83, v65, v81
	v_cvt_pk_bf16_f32 v84, v9, v11
	v_cvt_pk_bf16_f32 v85, v13, v15
	v_exp_f32_e32 v191, v90
	v_exp_f32_e32 v91, v91
	s_waitcnt lgkmcnt(4)
	v_mfma_f32_32x32x16_bf16 v[32:47], v[66:69], v[82:85], v[32:47]
	v_exp_f32_e32 v193, v92
	ds_read_b64_tr_b16 v[66:67], v194 offset:31744
	ds_read_b64_tr_b16 v[68:69], v194 offset:32256
	v_exp_f32_e32 v81, v95
	v_exp_f32_e32 v12, v70
	v_exp_f32_e32 v14, v71
	v_exp_f32_e32 v0, v72
	v_exp_f32_e32 v4, v73
	s_waitcnt lgkmcnt(4)
	v_mfma_f32_32x32x16_bf16 v[16:31], v[86:89], v[82:85], v[16:31]
	v_exp_f32_e32 v87, v93
	v_exp_f32_e32 v89, v94
	v_cvt_pk_bf16_f32 v70, v1, v5
	v_cvt_pk_bf16_f32 v71, v191, v91
	v_cvt_pk_bf16_f32 v72, v193, v87
	v_cvt_pk_bf16_f32 v73, v89, v81
	ds_read_b64_tr_b16 v[82:83], v194 offset:28672
	ds_read_b64_tr_b16 v[84:85], v194 offset:29184
	s_waitcnt lgkmcnt(4)
	v_mfma_f32_32x32x16_bf16 v[32:47], v[186:189], v[70:73], v[32:47]
	v_exp_f32_e32 v90, v75
	v_cvt_pk_bf16_f32 v75, v64, v80
	v_exp_f32_e32 v190, v74
	v_exp_f32_e32 v192, v76
	v_exp_f32_e32 v86, v77
	v_cvt_pk_bf16_f32 v74, v162, v164
	v_cvt_pk_bf16_f32 v76, v8, v10
	s_waitcnt lgkmcnt(2)
	v_mfma_f32_32x32x16_bf16 v[16:31], v[66:69], v[70:73], v[16:31]
	ds_read_b64_tr_b16 v[64:65], v194 offset:32768
	ds_read_b64_tr_b16 v[66:67], v194 offset:33280
	ds_read_b64_tr_b16 v[68:69], v194 offset:29696
	ds_read_b64_tr_b16 v[70:71], v194 offset:30208
	v_cvt_pk_bf16_f32 v77, v12, v14
	v_add_f32_e32 v6, v8, v6
	v_add_f32_e32 v7, v9, v7
	v_exp_f32_e32 v88, v78
	v_add_f32_e32 v6, v10, v6
	v_add_f32_e32 v7, v11, v7
	v_exp_f32_e32 v80, v79
	v_add_f32_e32 v6, v12, v6
	v_add_f32_e32 v7, v13, v7
	s_waitcnt lgkmcnt(4)
	v_mfma_f32_32x32x16_bf16 v[32:47], v[82:85], v[74:77], v[32:47]
	v_add_f32_e64 v10, v14, v6
	v_add_f32_e64 v11, v15, v7
	ds_read_b64_tr_b16 v[6:7], v194 offset:33792
	ds_read_b64_tr_b16 v[8:9], v194 offset:34304
	v_add_f32_e64 v10, v0, v10
	v_add_f32_e64 v11, v1, v11
	v_cvt_pk_bf16_f32 v12, v192, v86
	v_add_f32_e32 v10, v4, v10
	v_add_f32_e32 v11, v5, v11
	v_cvt_pk_bf16_f32 v13, v88, v80
	v_add_f32_e32 v14, v190, v10
	v_add_f32_e32 v15, v191, v11
	s_waitcnt lgkmcnt(4)
	v_mfma_f32_32x32x16_bf16 v[16:31], v[64:67], v[74:77], v[16:31]
	v_cvt_pk_bf16_f32 v10, v0, v4
	v_cvt_pk_bf16_f32 v11, v190, v90
	v_add_f32_e64 v0, v90, v14
	v_add_f32_e64 v1, v91, v15
	v_add_f32_e64 v0, v192, v0
	v_add_f32_e64 v1, v193, v1
	v_add_f32_e32 v0, v86, v0
	v_add_f32_e32 v1, v87, v1
	s_waitcnt lgkmcnt(2)
	v_mfma_f32_32x32x16_bf16 v[32:47], v[68:71], v[10:13], v[32:47]
	v_add_f32_e64 v0, v88, v0
	v_add_f32_e64 v1, v89, v1
	v_add_f32_e64 v0, v80, v0
	v_add_f32_e64 v1, v81, v1
	v_add_f32_e32 v0, v0, v1
	v_add_f32_e32 v184, v184, v0
	s_waitcnt lgkmcnt(0)
	v_mfma_f32_32x32x16_bf16 v[16:31], v[6:9], v[10:13], v[16:31]
	s_cmp_gt_i32 s41, s39
	s_cbranch_scc1 .LBB0_233

; template <int MODE, int NDG> ...
;     ...
;         float a = fmaxf(fmaxf(p0[0], p0[1]), p1[0]), b = fmaxf(fmaxf(p0[2], p0[3]), p1[1]); a = fmaxf(fmaxf(a, p1[2]), p1[3]);
; #pragma unroll
;         for (int r = 4; r < 16; r += 4) { a = fmaxf(fmaxf(a, p0[r]), p0[r + 1]); b = fmaxf(fmaxf(b, p0[r + 2]), p0[r + 3]); a = fmaxf(fmaxf(a, p1[r]), p1[r + 1]); b = fmaxf(fmaxf(b, p1[r + 2]), p1[r + 3]); }
;         float rm = fmaxf(a, b); rm = fmaxf(rm, xlane_partner(rm));
;         if (__any(rm > thr)) {
;             const float d = (thr < 0.f) ? ((rm > -INFINITY) ? rm : 0.f) : fmaxf(rm, 0.f);
;             m += d;
; #pragma unroll
;             for (int r = 0; r < 16; ++r) { p0[r] -= d; p1[r] -= d; }
;             if (thr >= 0.f) { const float f = __builtin_amdgcn_exp2f(-d); l *= f;
; #pragma unroll
;                 for (int dg = 0; dg < NDG; ++dg)
; #pragma unroll
;                     for (int r = 0; r < 16; ++r) o[dg][r] *= f; }
.LBB0_243:
	s_nop 8
	v_max_f32_e32 v0, v81, v81
	v_max_f32_e32 v1, v80, v80
	v_max_f32_e32 v0, v1, v0
	v_max3_f32 v1, v82, v83, v65
	v_max3_f32 v0, v0, v64, v66
	v_max3_f32 v0, v0, v67, v84
	v_max3_f32 v1, v1, v86, v87
	v_max3_f32 v0, v0, v85, v68
	v_max3_f32 v1, v1, v70, v71
	v_max3_f32 v0, v0, v69, v88
	v_max3_f32 v1, v1, v90, v91
	v_max3_f32 v0, v0, v89, v72
	v_max3_f32 v1, v1, v74, v75
	v_max3_f32 v0, v0, v73, v92
	v_max3_f32 v1, v1, v94, v95
	v_max3_f32 v0, v0, v93, v76
	v_max3_f32 v1, v1, v78, v79
	v_max3_f32 v0, v0, v77, v1
	v_mov_b32_e32 v1, v0
	v_mov_b32_e32 v3, v0
	s_nop 1
	v_permlane32_swap_b32_e32 v1, v3
	v_xor_b32_e32 v1, v1, v3
	v_xor_b32_e32 v1, v1, v0
	v_max_f32_e32 v1, v1, v1
	v_max_f32_e32 v0, v0, v1
	v_cmp_lt_f32_e32 vcc, s46, v0
	s_cbranch_vccz .LBB0_247
	v_cmp_lg_f32_e32 vcc, s85, v0
	v_cmp_nge_f32_e64 s[44:45], s46, 0
	s_nop 0
	v_cndmask_b32_e32 v1, 0, v0, vcc
	v_max_f32_e32 v0, v0, v0
	v_max_f32_e32 v0, 0, v0
	v_cmp_lt_f32_e64 vcc, s46, 0
	s_nop 1
	v_cndmask_b32_e32 v0, v0, v1, vcc
	s_and_b64 vcc, exec, s[44:45]
	s_cbranch_vccnz .LBB0_246
	v_exp_f32_e64 v4, -v0
	s_nop 0
	v_mul_f32_e32 v184, v184, v4
	v_mul_f32_e32 v46, v46, v4
	v_mul_f32_e32 v47, v47, v4
	v_mul_f32_e32 v44, v44, v4
	v_mul_f32_e32 v45, v45, v4
	v_mul_f32_e32 v42, v42, v4
	v_mul_f32_e32 v43, v43, v4
	v_mul_f32_e32 v40, v40, v4
	v_mul_f32_e32 v41, v41, v4
	v_mul_f32_e32 v38, v38, v4
	v_mul_f32_e32 v39, v39, v4
	v_mul_f32_e32 v36, v36, v4
	v_mul_f32_e32 v37, v37, v4
	v_mul_f32_e32 v34, v34, v4
	v_mul_f32_e32 v35, v35, v4
	v_mul_f32_e32 v32, v32, v4
	v_mul_f32_e32 v33, v33, v4
	v_mul_f32_e32 v30, v30, v4
	v_mul_f32_e32 v31, v31, v4
	v_mul_f32_e32 v28, v28, v4
	v_mul_f32_e32 v29, v29, v4
	v_mul_f32_e32 v26, v26, v4
	v_mul_f32_e32 v27, v27, v4
	v_mul_f32_e32 v24, v24, v4
	v_mul_f32_e32 v25, v25, v4
	v_mul_f32_e32 v22, v22, v4
	v_mul_f32_e32 v23, v23, v4
	v_mul_f32_e32 v20, v20, v4
	v_mul_f32_e32 v21, v21, v4
	v_mul_f32_e32 v18, v18, v4
	v_mul_f32_e32 v19, v19, v4
	v_mul_f32_e32 v16, v16, v4
	v_mul_f32_e32 v17, v17, v4

; __device__ __forceinline__ unsigned cvtpk(float lo, float hi) { f32x2 v = {lo, hi}; bf16x2_t b = __builtin_convertvector(v, bf16x2_t); return __builtin_bit_cast(unsigned, b); }
; #define LAS __attribute__((address_space(3)))
; template <int MODE, int NDG> ...
;     ...
;         float s0 = 0.f, s1 = 0.f;
; #pragma unroll
;         for (int r = 0; r < 16; ++r) { p0[r] = __builtin_amdgcn_exp2f(p0[r]); p1[r] = __builtin_amdgcn_exp2f(p1[r]); s0 += p0[r]; s1 += p1[r]; }
;         l += s0 + s1;
;         pw[0] = (u32x4){cvtpk(p0[0], p0[1]), cvtpk(p0[2], p0[3]), cvtpk(p0[4], p0[5]), cvtpk(p0[6], p0[7])};
;         pw[1] = (u32x4){cvtpk(p0[8], p0[9]), cvtpk(p0[10], p0[11]), cvtpk(p0[12], p0[13]), cvtpk(p0[14], p0[15])};
;         pw[2] = (u32x4){cvtpk(p1[0], p1[1]), cvtpk(p1[2], p1[3]), cvtpk(p1[4], p1[5]), cvtpk(p1[6], p1[7])};
;         pw[3] = (u32x4){cvtpk(p1[8], p1[9]), cvtpk(p1[10], p1[11]), cvtpk(p1[12], p1[13]), cvtpk(p1[14], p1[15])};
;     }
;     LAS const unsigned char* vp = vst + ((lane >> 4) & 1) * 32 + (lane & 3) * 8 + (4 * hi + ((lane & 15) >> 2)) * 64;
; #pragma unroll
;     for (int ks = 0; ks < 4; ++ks)
; #pragma unroll
;         for (int dg = 0; dg < NDG; ++dg) {
;             const bf16x8 vf = vfrag(vp + dg * 4096 + ks * 1024);
;             o[dg] = __builtin_amdgcn_mfma_f32_32x32x16_bf16(vf, __builtin_bit_cast(bf16x8, pw[ks]), o[dg], 0, 0, 0);
;         }
.LBB0_247:
	v_exp_f32_e32 v163, v80
	v_exp_f32_e32 v162, v64
	v_exp_f32_e32 v165, v81
	v_exp_f32_e32 v164, v65
	v_exp_f32_e32 v65, v82
	v_exp_f32_e32 v64, v66
	v_exp_f32_e32 v81, v83
	v_exp_f32_e32 v80, v67
	v_add3_u32 v3, s24, v172, v137
	v_pk_add_f32 v[0:1], v[162:163], 0 op_sel_hi:[1,0]
	v_add3_u32 v3, v3, v173, v174
	v_add_f32_e32 v0, v164, v0
	v_add_f32_e32 v1, v165, v1
	v_exp_f32_e32 v9, v84
	v_exp_f32_e32 v8, v68
	v_exp_f32_e32 v11, v85
	v_exp_f32_e32 v10, v69
	v_exp_f32_e32 v13, v86
	v_exp_f32_e32 v15, v87
	ds_read_b64_tr_b16 v[66:67], v3 offset:18432
	ds_read_b64_tr_b16 v[68:69], v3 offset:18944
	v_add_f32_e32 v0, v64, v0
	v_add_f32_e32 v1, v65, v1
	v_exp_f32_e32 v5, v89
	v_add_f32_e32 v6, v80, v0
	v_add_f32_e32 v7, v81, v1
	v_exp_f32_e32 v1, v88
	ds_read_b64_tr_b16 v[86:87], v3 offset:22528
	ds_read_b64_tr_b16 v[88:89], v3 offset:23040
	ds_read_b64_tr_b16 v[186:187], v3 offset:19456
	ds_read_b64_tr_b16 v[188:189], v3 offset:19968
	v_cvt_pk_bf16_f32 v82, v163, v165
	v_cvt_pk_bf16_f32 v83, v65, v81
	v_cvt_pk_bf16_f32 v84, v9, v11
	v_cvt_pk_bf16_f32 v85, v13, v15
	v_exp_f32_e32 v191, v90
	v_exp_f32_e32 v91, v91
	s_waitcnt lgkmcnt(4)
	v_mfma_f32_32x32x16_bf16 v[32:47], v[66:69], v[82:85], v[32:47]
	v_exp_f32_e32 v193, v92
	ds_read_b64_tr_b16 v[66:67], v3 offset:23552
	ds_read_b64_tr_b16 v[68:69], v3 offset:24064
	v_exp_f32_e32 v81, v95
	v_exp_f32_e32 v12, v70
	v_exp_f32_e32 v14, v71
	v_exp_f32_e32 v0, v72
	v_exp_f32_e32 v4, v73
	s_waitcnt lgkmcnt(4)
	v_mfma_f32_32x32x16_bf16 v[16:31], v[86:89], v[82:85], v[16:31]
	v_exp_f32_e32 v87, v93
	v_exp_f32_e32 v89, v94
	v_cvt_pk_bf16_f32 v70, v1, v5
	v_cvt_pk_bf16_f32 v71, v191, v91
	v_cvt_pk_bf16_f32 v72, v193, v87
	v_cvt_pk_bf16_f32 v73, v89, v81
	ds_read_b64_tr_b16 v[82:83], v3 offset:20480
	ds_read_b64_tr_b16 v[84:85], v3 offset:20992
	s_waitcnt lgkmcnt(4)
	v_mfma_f32_32x32x16_bf16 v[32:47], v[186:189], v[70:73], v[32:47]
	v_exp_f32_e32 v90, v75
	v_cvt_pk_bf16_f32 v75, v64, v80
	v_exp_f32_e32 v190, v74
	v_exp_f32_e32 v192, v76
	v_exp_f32_e32 v86, v77
	v_cvt_pk_bf16_f32 v74, v162, v164
	v_cvt_pk_bf16_f32 v76, v8, v10
	s_waitcnt lgkmcnt(2)
	v_mfma_f32_32x32x16_bf16 v[16:31], v[66:69], v[70:73], v[16:31]
	ds_read_b64_tr_b16 v[64:65], v3 offset:24576
	ds_read_b64_tr_b16 v[66:67], v3 offset:25088
	ds_read_b64_tr_b16 v[68:69], v3 offset:21504
	ds_read_b64_tr_b16 v[70:71], v3 offset:22016
	v_cvt_pk_bf16_f32 v77, v12, v14
	v_add_f32_e32 v6, v8, v6
	v_add_f32_e32 v7, v9, v7
	v_exp_f32_e32 v88, v78
	v_add_f32_e32 v6, v10, v6
	v_add_f32_e32 v7, v11, v7
	v_exp_f32_e32 v80, v79
	v_add_f32_e32 v6, v12, v6
	v_add_f32_e32 v7, v13, v7
	s_waitcnt lgkmcnt(4)
	v_mfma_f32_32x32x16_bf16 v[32:47], v[82:85], v[74:77], v[32:47]
	v_add_f32_e64 v10, v14, v6
	v_add_f32_e64 v11, v15, v7
	ds_read_b64_tr_b16 v[6:7], v3 offset:25600
	ds_read_b64_tr_b16 v[8:9], v3 offset:26112
	v_add_f32_e64 v10, v0, v10
	v_add_f32_e64 v11, v1, v11
	v_cvt_pk_bf16_f32 v12, v192, v86
	v_add_f32_e32 v10, v4, v10
	v_add_f32_e32 v11, v5, v11
	v_cvt_pk_bf16_f32 v13, v88, v80
	v_add_f32_e32 v14, v190, v10
	v_add_f32_e32 v15, v191, v11
	s_waitcnt lgkmcnt(4)
	v_mfma_f32_32x32x16_bf16 v[16:31], v[64:67], v[74:77], v[16:31]
	v_cvt_pk_bf16_f32 v10, v0, v4
	v_cvt_pk_bf16_f32 v11, v190, v90
	v_add_f32_e64 v0, v90, v14
	v_add_f32_e64 v1, v91, v15
	v_add_f32_e64 v0, v192, v0
	v_add_f32_e64 v1, v193, v1
	v_add_f32_e32 v0, v86, v0
	v_add_f32_e32 v1, v87, v1
	s_waitcnt lgkmcnt(2)
	v_mfma_f32_32x32x16_bf16 v[32:47], v[68:71], v[10:13], v[32:47]
	v_add_f32_e64 v0, v88, v0
	v_add_f32_e64 v1, v89, v1
	v_add_f32_e64 v0, v80, v0
	v_add_f32_e64 v1, v81, v1
	v_add_f32_e32 v0, v0, v1
	v_add_f32_e32 v184, v184, v0
	s_waitcnt lgkmcnt(0)
	v_mfma_f32_32x32x16_bf16 v[16:31], v[6:9], v[10:13], v[16:31]
	s_andn2_b64 vcc, exec, s[22:23]
	s_cbranch_vccnz .LBB0_251

; template <int MODE, int NDG> ...
;     ...
;         for (int r = 0; r < 16; ++r) { p0[r] = __builtin_amdgcn_rcpf(1.0f + __builtin_amdgcn_exp2f(p0[r])); p1[r] = __builtin_amdgcn_rcpf(1.0f + __builtin_amdgcn_exp2f(p1[r])); }
;         float x1[8], x0[8], GG[8], EG[8];
; #pragma unroll
;         for (int j = 0; j < 8; ++j) {
;             const int g = j & 3; float a3, a2, a1, a0;
;             if (j < 4) { a3 = p0[4 * g + 3]; a2 = p0[4 * g + 2]; a1 = p0[4 * g + 1]; a0 = p0[4 * g]; } else { a3 = p1[4 * g + 3]; a2 = p1[4 * g + 2]; a1 = p1[4 * g + 1]; a0 = p1[4 * g]; }
;             x1[j] = a3 * a2; x0[j] = x1[j] * a1; const float G = x0[j] * a0;
;             const float Gp = xlane_partner(G);
;             GG[j] = G * Gp; EG[j] = hi ? 1.0f : Gp;
;         }
;         float T = R; float w[32];
; #pragma unroll
;         for (int j = 7; j >= 0; --j) {
;             const float E = T * EG[j]; T *= GG[j];
;             const int g = j & 3; float a3, a2, a1, a0;
;             if (j < 4) { a3 = p0[4 * g + 3]; a2 = p0[4 * g + 2]; a1 = p0[4 * g + 1]; a0 = p0[4 * g]; } else { a3 = p1[4 * g + 3]; a2 = p1[4 * g + 2]; a1 = p1[4 * g + 1]; a0 = p1[4 * g]; }
;             w[4 * j + 3] = (1.0f - a3) * E; w[4 * j + 2] = (1.0f - a2) * (E * a3); w[4 * j + 1] = (1.0f - a1) * (E * x1[j]); w[4 * j] = (1.0f - a0) * (E * x0[j]);
;         }
.LBB0_261:
	s_nop 8
	v_exp_f32_e32 v36, v36
	v_exp_f32_e32 v37, v37
	v_exp_f32_e32 v52, v52
	v_add_f32_e32 v36, 1.0, v36
	v_add_f32_e32 v37, 1.0, v37
	v_add_f32_e32 v152, 1.0, v52
	v_rcp_f32_e32 v52, v36
	v_exp_f32_e32 v36, v53
	v_rcp_f32_e32 v53, v37
	v_exp_f32_e32 v37, v38
	v_exp_f32_e32 v38, v61
	v_add_f32_e32 v36, 1.0, v36
	v_rcp_f32_e32 v169, v36
	v_add_f32_e32 v37, 1.0, v37
	v_exp_f32_e32 v36, v54
	v_rcp_f32_e32 v54, v37
	v_exp_f32_e32 v37, v39
	v_exp_f32_e32 v39, v62
	v_add_f32_e32 v36, 1.0, v36
	v_rcp_f32_e32 v154, v36
	v_add_f32_e32 v37, 1.0, v37
	v_exp_f32_e32 v36, v55
	v_rcp_f32_e32 v55, v37
	v_exp_f32_e32 v37, v40
	v_add_f32_e32 v39, 1.0, v39
	v_add_f32_e32 v36, 1.0, v36
	v_rcp_f32_e32 v155, v36
	v_add_f32_e32 v37, 1.0, v37
	v_rcp_f32_e32 v170, v37
	v_exp_f32_e32 v37, v41
	v_exp_f32_e32 v36, v56
	v_exp_f32_e32 v40, v65
	v_exp_f32_e32 v41, v66
	v_add_f32_e32 v37, 1.0, v37
	v_rcp_f32_e32 v171, v37
	v_exp_f32_e32 v37, v42
	v_add_f32_e32 v36, 1.0, v36
	v_rcp_f32_e32 v172, v36
	v_exp_f32_e32 v36, v57
	v_add_f32_e32 v37, 1.0, v37
	v_rcp_f32_e32 v174, v37
	v_exp_f32_e32 v37, v43
	v_rcp_f32_e32 v42, v39
	v_exp_f32_e32 v39, v63
	v_add_f32_e32 v36, 1.0, v36
	v_add_f32_e32 v37, 1.0, v37
	v_rcp_f32_e32 v175, v37
	v_exp_f32_e32 v37, v44
	v_rcp_f32_e32 v173, v36
	v_exp_f32_e32 v36, v58
	v_add_f32_e32 v39, 1.0, v39
	v_add_f32_e32 v37, 1.0, v37
	v_rcp_f32_e32 v176, v37
	v_exp_f32_e32 v37, v45
	v_rcp_f32_e32 v43, v39
	v_exp_f32_e32 v39, v64
	v_exp_f32_e32 v44, v67
	v_add_f32_e32 v37, 1.0, v37
	v_rcp_f32_e32 v177, v37
	v_exp_f32_e32 v37, v46
	v_add_f32_e32 v36, 1.0, v36
	v_rcp_f32_e32 v156, v36
	v_exp_f32_e32 v36, v59
	v_add_f32_e32 v37, 1.0, v37
	v_rcp_f32_e32 v178, v37
	v_exp_f32_e32 v37, v47
	v_add_f32_e32 v40, 1.0, v40
	v_exp_f32_e32 v45, v51
	v_add_f32_e32 v36, 1.0, v36
	v_add_f32_e32 v37, 1.0, v37
	v_rcp_f32_e32 v179, v37
	v_exp_f32_e32 v37, v48
	v_add_f32_e32 v38, 1.0, v38
	v_add_f32_e32 v39, 1.0, v39
	v_rcp_f32_e32 v157, v36
	v_add_f32_e32 v37, 1.0, v37
	v_rcp_f32_e32 v64, v37
	v_exp_f32_e32 v37, v49
	v_rcp_f32_e32 v49, v40
	v_add_f32_e32 v40, 1.0, v41
	v_add_f32_e32 v41, 1.0, v44
	v_add_f32_e32 v37, 1.0, v37
	v_rcp_f32_e32 v65, v37
	v_exp_f32_e32 v37, v50
	v_rcp_f32_e32 v40, v40
	v_rcp_f32_e32 v41, v41
	v_exp_f32_e32 v36, v60
	v_rcp_f32_e32 v38, v38
	v_rcp_f32_e32 v39, v39
	v_add_f32_e32 v37, 1.0, v37
	v_rcp_f32_e32 v66, v37
	v_add_f32_e32 v37, 1.0, v45
	v_mul_f32_e32 v45, v41, v40
	v_mov_b32_e32 v48, v43
	v_mov_b32_e32 v44, v42
	v_mul_f32_e32 v46, v48, v44
	v_mul_f32_e32 v47, v49, v45
	v_add_f32_e32 v36, 1.0, v36
	v_mul_f32_e32 v56, v38, v46
	v_mul_f32_e32 v57, v39, v47
	v_rcp_f32_e32 v36, v36
	v_rcp_f32_e32 v67, v37
	v_pk_add_f32 v[50:51], v[42:43], 1.0 op_sel_hi:[1,0] neg_lo:[1,0] neg_hi:[1,0]
	v_mov_b32_e32 v37, v57
	v_mov_b32_e32 v42, v57
	s_nop 1
	v_permlane32_swap_b32_e32 v37, v42
	v_xor_b32_e32 v37, v37, v42
	v_xor_b32_e32 v37, v37, v57
	v_mul_f32_e32 v58, v36, v56
	v_mul_f32_e32 v59, v37, v57
	v_mul_f32_e32 v181, v157, v156
	v_mov_b32_e32 v42, v58
	v_mov_b32_e32 v44, v58
	s_nop 1
	v_permlane32_swap_b32_e32 v42, v44
	v_rcp_f32_e32 v168, v152
	v_xor_b32_e32 v42, v42, v44
	v_mul_f32_e32 v180, v173, v181
	v_xor_b32_e32 v152, v42, v58
	v_mul_f32_e32 v182, v172, v180
	v_mul_f32_e32 v60, v58, v152
	v_mul_f32_e32 v61, v59, v153
	v_mov_b32_e32 v58, v36
	v_mov_b32_e32 v59, v38
	v_mov_b32_e32 v36, v182
	v_mov_b32_e32 v38, v182
	v_mul_f32_e32 v187, v155, v154
	s_nop 0
	v_permlane32_swap_b32_e32 v36, v38
	v_mul_f32_e32 v186, v169, v187
	v_xor_b32_e32 v36, v36, v38
	v_mul_f32_e32 v188, v168, v186
	v_xor_b32_e32 v184, v36, v182
	v_mov_b32_e32 v36, v188
	v_mov_b32_e32 v44, v188
	v_mul_f32_e32 v193, v67, v66
	s_nop 0
	v_permlane32_swap_b32_e32 v36, v44
	v_mul_f32_e32 v192, v65, v193
	v_xor_b32_e32 v36, v36, v44
	v_mul_f32_e32 v194, v64, v192
	v_xor_b32_e32 v190, v36, v188
	v_mov_b32_e32 v36, v194
	v_mov_b32_e32 v48, v194
	v_mul_f32_e32 v205, v179, v178
	v_mov_b32_e32 v183, v60
	v_mov_b32_e32 v185, v61
	v_permlane32_swap_b32_e32 v36, v48
	v_mul_f32_e32 v204, v177, v205
	v_mul_f32_e32 v182, v182, v184
	v_mul_f32_e32 v183, v183, v185
	v_xor_b32_e32 v36, v36, v48
	v_mul_f32_e32 v206, v176, v204
	v_mov_b32_e32 v189, v182
	v_mov_b32_e32 v191, v183
	v_xor_b32_e32 v202, v36, v194
	v_mov_b32_e32 v36, v206
	v_mov_b32_e32 v57, v206
	v_mul_f32_e32 v211, v175, v174
	v_mul_f32_e32 v188, v188, v190
	v_mul_f32_e32 v189, v189, v191
	v_permlane32_swap_b32_e32 v36, v57
	v_mul_f32_e32 v210, v171, v211
	v_mov_b32_e32 v195, v188
	v_mov_b32_e32 v203, v189
	v_xor_b32_e32 v36, v36, v57
	v_mul_f32_e32 v212, v170, v210
	v_mul_f32_e32 v194, v194, v202
	v_mul_f32_e32 v195, v195, v203
	v_xor_b32_e32 v208, v36, v206
	v_mov_b32_e32 v36, v212
	v_mov_b32_e32 v60, v212
	v_mov_b32_e32 v207, v194
	v_mov_b32_e32 v209, v195
	v_permlane32_swap_b32_e32 v36, v60
	v_mul_f32_e32 v206, v206, v208
	v_mul_f32_e32 v207, v207, v209
	v_xor_b32_e32 v36, v36, v60
	v_xor_b32_e32 v214, v36, v212
	v_mov_b32_e32 v213, v206
	v_mov_b32_e32 v215, v207
	v_mul_f32_e32 v212, v212, v214
	v_mul_f32_e32 v213, v213, v215
	v_cndmask_b32_e64 v36, 1.0, v214, s[4:5]
	v_cndmask_b32_e64 v57, 1.0, v208, s[4:5]
	v_mul_f32_e32 v36, v36, v213
	v_cndmask_b32_e64 v48, 1.0, v202, s[4:5]
	v_pk_add_f32 v[208:209], v[174:175], 1.0 op_sel_hi:[1,0] neg_lo:[1,0] neg_hi:[1,0]
	v_mul_f32_e32 v210, v210, v36
	v_mul_f32_e32 v211, v211, v36
	v_mul_f32_e32 v174, v175, v36
	v_mov_b32_e32 v175, v36
	v_mul_f32_e32 v36, v57, v207
	v_pk_add_f32 v[202:203], v[178:179], 1.0 op_sel_hi:[1,0] neg_lo:[1,0] neg_hi:[1,0]
	v_mul_f32_e32 v204, v204, v36
	v_mul_f32_e32 v205, v205, v36
	v_mul_f32_e32 v178, v179, v36
	v_mov_b32_e32 v179, v36
; __device__ __forceinline__ unsigned cvtpk(float lo, float hi) { f32x2 v = {lo, hi}; bf16x2_t b = __builtin_convertvector(v, bf16x2_t); return __builtin_bit_cast(unsigned, b); }
; #define LAS __attribute__((address_space(3)))
; template <int MODE, int NDG> ...
;     ...
;         float T = R; float w[32];
; #pragma unroll
;         for (int j = 7; j >= 0; --j) {
;             const float E = T * EG[j]; T *= GG[j];
;             const int g = j & 3; float a3, a2, a1, a0;
;             if (j < 4) { a3 = p0[4 * g + 3]; a2 = p0[4 * g + 2]; a1 = p0[4 * g + 1]; a0 = p0[4 * g]; } else { a3 = p1[4 * g + 3]; a2 = p1[4 * g + 2]; a1 = p1[4 * g + 1]; a0 = p1[4 * g]; }
;             w[4 * j + 3] = (1.0f - a3) * E; w[4 * j + 2] = (1.0f - a2) * (E * a3); w[4 * j + 1] = (1.0f - a1) * (E * x1[j]); w[4 * j] = (1.0f - a0) * (E * x0[j]);
;         }
;         R = T;
; #pragma unroll
;         for (int ks = 0; ks < 4; ++ks) { pw[ks].x = cvtpk(w[8 * ks], w[8 * ks + 1]); pw[ks].y = cvtpk(w[8 * ks + 2], w[8 * ks + 3]); pw[ks].z = cvtpk(w[8 * ks + 4], w[8 * ks + 5]); pw[ks].w = cvtpk(w[8 * ks + 6], w[8 * ks + 7]); }
;     ...
;     LAS const unsigned char* vp = vst + ((lane >> 4) & 1) * 32 + (lane & 3) * 8 + (4 * hi + ((lane & 15) >> 2)) * 64;
; #pragma unroll
;     for (int ks = 0; ks < 4; ++ks)
; #pragma unroll
;         for (int dg = 0; dg < NDG; ++dg) {
;             const bf16x8 vf = vfrag(vp + dg * 4096 + ks * 1024);
;             o[dg] = __builtin_amdgcn_mfma_f32_32x32x16_bf16(vf, __builtin_bit_cast(bf16x8, pw[ks]), o[dg], 0, 0, 0);
;         }
	v_mul_f32_e32 v36, v48, v195
	v_pk_add_f32 v[64:65], v[64:65], 1.0 op_sel_hi:[1,0] neg_lo:[1,0] neg_hi:[1,0]
	v_mul_f32_e32 v192, v192, v36
	v_mul_f32_e32 v193, v193, v36
	v_cndmask_b32_e64 v44, 1.0, v190, s[4:5]
	v_pk_add_f32 v[190:191], v[66:67], 1.0 op_sel_hi:[1,0] neg_lo:[1,0] neg_hi:[1,0]
	v_mul_f32_e32 v192, v64, v192
	v_mul_f32_e32 v193, v65, v193
	v_mul_f32_e32 v64, v67, v36
	v_mul_f32_e32 v67, v55, v54
	v_mov_b32_e32 v65, v36
	v_mul_f32_e32 v36, v44, v189
	v_mul_f32_e32 v66, v53, v67
	v_cndmask_b32_e64 v38, 1.0, v184, s[4:5]
	v_pk_add_f32 v[184:185], v[154:155], 1.0 op_sel_hi:[1,0] neg_lo:[1,0] neg_hi:[1,0]
	v_pk_add_f32 v[168:169], v[168:169], 1.0 op_sel_hi:[1,0] neg_lo:[1,0] neg_hi:[1,0]
	v_mul_f32_e32 v190, v190, v64
	v_mul_f32_e32 v191, v191, v65
	v_mul_f32_e32 v64, v186, v36
	v_mul_f32_e32 v65, v187, v36
	v_mul_f32_e32 v154, v52, v66
	v_mul_f32_e32 v186, v168, v64
	v_mul_f32_e32 v187, v169, v65
	v_mul_f32_e32 v64, v155, v36
	v_mov_b32_e32 v65, v36
	v_mul_f32_e32 v36, v38, v183
	v_mov_b32_e32 v38, v154
	v_mov_b32_e32 v44, v154
	s_nop 1
	v_permlane32_swap_b32_e32 v38, v44
	v_xor_b32_e32 v38, v38, v44
	v_pk_add_f32 v[62:63], v[156:157], 1.0 op_sel_hi:[1,0] neg_lo:[1,0] neg_hi:[1,0]
	v_mul_f32_e32 v184, v184, v64
	v_mul_f32_e32 v185, v185, v65
	v_mul_f32_e32 v64, v180, v36
	v_mul_f32_e32 v65, v181, v36
	v_mul_f32_e32 v180, v157, v36
	v_xor_b32_e32 v156, v38, v154
	v_mov_b32_e32 v155, v212
	v_mov_b32_e32 v157, v213
	v_mul_f32_e32 v182, v154, v156
	v_mul_f32_e32 v183, v155, v157
	v_cndmask_b32_e64 v38, 1.0, v156, s[4:5]
	v_mul_f32_e32 v155, v38, v183
	v_pk_add_f32 v[172:173], v[172:173], 1.0 op_sel_hi:[1,0] neg_lo:[1,0] neg_hi:[1,0]
	v_mov_b32_e32 v38, v155
	v_mul_f32_e32 v172, v172, v64
	v_mul_f32_e32 v173, v173, v65
	v_pk_add_f32 v[64:65], v[54:55], 1.0 op_sel_hi:[1,0] neg_lo:[1,0] neg_hi:[1,0]
	v_mul_f32_e32 v154, v55, v155
	v_pk_add_f32 v[52:53], v[52:53], 1.0 op_sel_hi:[1,0] neg_lo:[1,0] neg_hi:[1,0]
	v_mul_f32_e32 v54, v66, v38
	v_mul_f32_e32 v55, v67, v38
	v_pk_add_f32 v[170:171], v[170:171], 1.0 op_sel_hi:[1,0] neg_lo:[1,0] neg_hi:[1,0]
	v_mul_f32_e32 v156, v64, v154
	v_mul_f32_e32 v157, v65, v155
	v_mul_f32_e32 v64, v52, v54
	v_mul_f32_e32 v65, v53, v55
	ds_read_b64_tr_b16 v[52:53], v163 offset:9216
	ds_read_b64_tr_b16 v[54:55], v163 offset:9728
	v_mul_f32_e32 v170, v170, v210
	v_mul_f32_e32 v171, v171, v211
	v_cvt_pk_bf16_f32 v64, v64, v65
	v_cvt_pk_bf16_f32 v65, v156, v157
	v_cvt_pk_bf16_f32 v66, v170, v171
	ds_read_b64_tr_b16 v[154:155], v163 offset:13312
	ds_read_b64_tr_b16 v[156:157], v163 offset:13824
	ds_read_b64_tr_b16 v[168:169], v163 offset:10240
	ds_read_b64_tr_b16 v[170:171], v163 offset:10752
	v_mul_f32_e32 v174, v208, v174
	v_mul_f32_e32 v175, v209, v175
	v_cndmask_b32_e64 v42, 1.0, v152, s[4:5]
	v_cvt_pk_bf16_f32 v67, v174, v175
	v_pk_add_f32 v[176:177], v[176:177], 1.0 op_sel_hi:[1,0] neg_lo:[1,0] neg_hi:[1,0]
	v_mov_b32_e32 v181, v36
	s_waitcnt lgkmcnt(4)
	v_mfma_f32_32x32x16_bf16 v[20:35], v[52:55], v[64:67], v[20:35]
	ds_read_b64_tr_b16 v[52:53], v163 offset:14336
	ds_read_b64_tr_b16 v[54:55], v163 offset:14848
	v_mul_f32_e32 v36, v42, v61
	v_mov_b32_e32 v57, v46
	v_add_f32_e64 v58, -v58, 1.0
	v_add_f32_e64 v59, -v59, 1.0
	v_mul_f32_e32 v176, v176, v204
	v_mul_f32_e32 v177, v177, v205
	v_mul_f32_e32 v178, v202, v178
	v_mul_f32_e32 v179, v203, v179
	v_mul_f32_e32 v56, v56, v36
	v_mul_f32_e32 v57, v57, v36
	s_waitcnt lgkmcnt(4)
	v_mfma_f32_32x32x16_bf16 v[4:19], v[154:157], v[64:67], v[4:19]
	v_mul_f32_e64 v60, v58, v56
	v_mul_f32_e64 v61, v59, v57
	v_cvt_pk_bf16_f32 v56, v176, v177
	v_cvt_pk_bf16_f32 v57, v178, v179
	v_cvt_pk_bf16_f32 v58, v192, v193
	v_cvt_pk_bf16_f32 v59, v190, v191
	v_mul_f32_e32 v42, v43, v36
	v_mov_b32_e32 v43, v36
	s_waitcnt lgkmcnt(2)
	v_mfma_f32_32x32x16_bf16 v[20:35], v[168:171], v[56:59], v[20:35]
	v_mov_b32_e32 v48, v39
	v_mul_f32_e64 v64, v50, v42
	v_mul_f32_e64 v65, v51, v43
	v_add_f32_e64 v42, -v48, 1.0
	v_add_f32_e64 v43, -v49, 1.0
	ds_read_b64_tr_b16 v[48:49], v163 offset:11264
	ds_read_b64_tr_b16 v[50:51], v163 offset:11776
	v_mul_f32_e32 v62, v62, v180
	v_mul_f32_e32 v63, v63, v181
	v_cndmask_b32_e64 v44, 1.0, v37, s[4:5]
	v_cvt_pk_bf16_f32 v36, v186, v187
	s_waitcnt lgkmcnt(2)
	v_mfma_f32_32x32x16_bf16 v[4:19], v[52:55], v[56:59], v[4:19]
	ds_read_b64_tr_b16 v[52:53], v163 offset:15360
	ds_read_b64_tr_b16 v[54:55], v163 offset:15872
	ds_read_b64_tr_b16 v[56:57], v163 offset:12288
	ds_read_b64_tr_b16 v[58:59], v163 offset:12800
	v_cvt_pk_bf16_f32 v37, v184, v185
	v_cvt_pk_bf16_f32 v38, v172, v173
	v_cvt_pk_bf16_f32 v39, v62, v63
	v_mul_f32_e32 v46, v153, v44
	v_mov_b32_e32 v44, v47
	v_mul_f32_e32 v44, v44, v46
	v_mul_f32_e32 v45, v45, v46
	s_waitcnt lgkmcnt(4)
	v_mfma_f32_32x32x16_bf16 v[20:35], v[48:51], v[36:39], v[20:35]
	v_mul_f32_e64 v48, v42, v44
	v_mul_f32_e64 v49, v43, v45
	ds_read_b64_tr_b16 v[42:43], v163 offset:16384
	ds_read_b64_tr_b16 v[44:45], v163 offset:16896
	v_mul_f32_e32 v50, v41, v46
	v_mov_b32_e32 v51, v46
	v_mul_f32_e32 v153, v182, v183
	v_cmp_le_f32_e32 vcc, s79, v153
	s_waitcnt lgkmcnt(4)
	v_mfma_f32_32x32x16_bf16 v[4:19], v[52:55], v[36:39], v[4:19]
	v_add_f32_e64 v36, -v40, 1.0
	v_add_f32_e64 v37, -v41, 1.0
	v_cvt_pk_bf16_f32 v38, v48, v49
	v_mul_f32_e64 v40, v36, v50
	v_mul_f32_e64 v41, v37, v51
	v_cvt_pk_bf16_f32 v36, v60, v61
	v_cvt_pk_bf16_f32 v37, v64, v65
	v_cvt_pk_bf16_f32 v39, v40, v41
	s_waitcnt lgkmcnt(2)
	s_nop 0
	v_mfma_f32_32x32x16_bf16 v[20:35], v[56:59], v[36:39], v[20:35]
	s_waitcnt lgkmcnt(0)
	v_mfma_f32_32x32x16_bf16 v[4:19], v[42:45], v[36:39], v[4:19]
	s_cbranch_vccz .LBB0_256
	s_andn2_b64 vcc, exec, s[96:97]
	s_cbranch_vccnz .LBB0_264
	s_waitcnt vmcnt(15)
	ds_write_b128 v164, v[84:87]
	s_waitcnt vmcnt(7)
	ds_write_b128 v166, v[116:119] offset:9216
	ds_write_b128 v164, v[88:91] offset:1152
	s_waitcnt vmcnt(6)
	ds_write_b128 v166, v[120:123] offset:10240
	ds_write_b128 v164, v[92:95] offset:2304
	s_waitcnt vmcnt(5)
	ds_write_b128 v166, v[124:127] offset:11264
	ds_write_b128 v164, v[96:99] offset:3456
	s_waitcnt vmcnt(4)
	ds_write_b128 v166, v[128:131] offset:12288
	ds_write_b128 v164, v[100:103] offset:4608
	s_waitcnt vmcnt(3)
	ds_write_b128 v166, v[132:135] offset:13312
	ds_write_b128 v164, v[104:107] offset:5760
	s_waitcnt vmcnt(2)
	ds_write_b128 v166, v[136:139] offset:14336
	ds_write_b128 v164, v[108:111] offset:6912
	s_waitcnt vmcnt(1)
	ds_write_b128 v166, v[140:143] offset:15360
	ds_write_b128 v164, v[112:115] offset:8064
	s_waitcnt vmcnt(0)
	ds_write_b128 v166, v[144:147] offset:16384
